# prologue: x f32->bf16 rows converted 8 floats per lane with dwordx4 stores (half the store instructions; global stores are issue-bound per instruction)
# baseline (speedup 1.0000x reference)
.LBB0_90:
	s_or_b64 exec, exec, s[6:7]
	s_mov_b32 s3, 0x10200
	v_cmp_gt_i32_e32 vcc, s3, v196
	v_ashrrev_i32_e32 v197, 31, v196
	v_lshlrev_b32_e32 v2, 2, v217
	s_and_saveexec_b64 s[4:5], vcc
	s_cbranch_execz .LBB0_97
	v_mov_b32_e32 v5, 0
	v_lshlrev_b32_e32 v4, 4, v217
	v_lshl_add_u64 v[6:7], s[10:11], 0, v[4:5]
	s_mov_b64 s[6:7], 0x6800000
	s_ashr_i32 s31, s30, 31
	v_lshl_add_u64 v[6:7], v[6:7], 0, s[6:7]
	v_lshlrev_b64 v[8:9], 12, v[196:197]
	s_lshl_b64 s[6:7], s[30:31], 12
	s_mov_b64 s[12:13], 0
	s_mov_b32 s3, 0xffff
	v_lshlrev_b32_e32 v10, 3, v2
	v_mov_b32_e32 v11, v5
	s_mov_b32 s16, 0x101ff
	v_mov_b64_e32 v[12:13], v[196:197]
	s_branch .LBB0_93
.LBB0_92:
	s_or_b64 exec, exec, s[14:15]
	v_lshl_add_u64 v[22:23], v[14:15], 0, v[10:11]
	global_load_dwordx4 v[18:21], v[22:23], off
	global_load_dwordx4 v[26:29], v[22:23], off offset:16
	global_load_dwordx4 v[30:33], v[22:23], off offset:2048
	global_load_dwordx4 v[34:37], v[22:23], off offset:2064
	v_lshlrev_b64 v[14:15], 11, v[16:17]
	v_lshl_add_u64 v[24:25], v[6:7], 0, v[14:15]
	v_lshl_add_u64 v[12:13], v[12:13], 0, s[30:31]
	v_cmp_lt_i32_e32 vcc, s16, v12
	s_or_b64 s[12:13], vcc, s[12:13]
	v_lshl_add_u64 v[8:9], v[8:9], 0, s[6:7]
	s_waitcnt vmcnt(2)
	v_cvt_pk_bf16_f32 v38, v18, v19
	v_cvt_pk_bf16_f32 v39, v20, v21
	v_cvt_pk_bf16_f32 v40, v26, v27
	v_cvt_pk_bf16_f32 v41, v28, v29
	global_store_dwordx4 v[24:25], v[38:41], off
	s_waitcnt vmcnt(1)
	v_cvt_pk_bf16_f32 v42, v30, v31
	v_cvt_pk_bf16_f32 v43, v32, v33
	v_cvt_pk_bf16_f32 v44, v34, v35
	v_cvt_pk_bf16_f32 v45, v36, v37
	global_store_dwordx4 v[24:25], v[42:45], off offset:1024
	s_andn2_b64 exec, exec, s[12:13]
	s_cbranch_execz .LBB0_97
